# re-measure of barrier variant B (v37) for statistics
# speedup vs baseline: 1.0040x; 1.0040x over previous
.LBB0_55:
	s_or_b64 exec, exec, s[4:5]
	buffer_inv sc1
	v_cvt_f32_u32_e32 v3, v0
	s_waitcnt vmcnt(1)
	v_readfirstlane_b32 s2, v2
	v_sub_u32_e32 v2, 0, v0
	v_readlane_b32 s22, v251, 50
	v_rcp_iflag_f32_e32 v3, v3
	v_add_u32_e32 v1, s2, v1
	v_add_u32_e32 v4, 1, v1
	v_readlane_b32 s23, v251, 51
	v_mul_f32_e32 v3, 0x4f7ffffe, v3
	v_cvt_u32_f32_e32 v3, v3
	s_mov_b64 s[4:5], -1
	v_mul_lo_u32 v2, v2, v3
	v_mul_hi_u32 v2, v3, v2
	v_add_u32_e32 v2, v3, v2
	v_mul_hi_u32 v2, v1, v2
	v_mul_lo_u32 v3, v2, v0
	v_sub_u32_e32 v1, v1, v3
	v_add_u32_e32 v5, 1, v2
	v_sub_u32_e32 v3, v1, v0
	v_cmp_ge_u32_e32 vcc, v1, v0
	s_nop 1
	v_cndmask_b32_e32 v2, v2, v5, vcc
	v_cndmask_b32_e32 v1, v1, v3, vcc
	v_add_u32_e32 v3, 1, v2
	v_cmp_ge_u32_e32 vcc, v1, v0
	s_nop 1
	v_cndmask_b32_e32 v2, v2, v3, vcc
	v_mul_lo_u32 v1, v0, v2
	v_add_u32_e32 v0, v1, v0
	v_cmp_ne_u32_e32 vcc, v4, v0
	v_mov_b64_e32 v[0:1], s[22:23]
	s_and_saveexec_b64 s[2:3], vcc
	v_readlane_b32 s20, v251, 46
	v_readlane_b32 s21, v251, 47
	s_cbranch_execz .LBB0_67
	global_load_dword v0, v177, s[22:23] sc1
	s_mov_b64 s[6:7], 0
	s_waitcnt vmcnt(0)
	v_cmp_eq_u32_e32 vcc, v0, v2
	s_and_saveexec_b64 s[4:5], vcc
	s_cbranch_execz .LBB0_66
	s_mov_b32 s16, 1
	s_branch .LBB0_59
